# prologue mod GEMV: the 1024 second-round split-K items cut into two K halves so every wave runs 1.5 items instead of 2 or 1
# speedup vs baseline: 1.0216x; 1.0026x over previous
.LBB0_23:
	s_or_b64 exec, exec, s[4:5]
	s_ashr_i32 s22, s8, 6
	s_lshl_b32 s90, s91, 3
	s_lshl_b32 s18, s94, 3
	s_add_i32 s19, s22, s90
	s_add_u32 s92, s34, 0x10000
	s_addc_u32 s93, s35, 0
	s_waitcnt vmcnt(3)
	v_and_b32_e32 v16, 63, v1
	s_cmpk_gt_i32 s19, 0xbff
	s_waitcnt lgkmcnt(0)
	s_barrier
	s_cbranch_scc1 .LBB0_30
	s_movk_i32 s6, 0x6000
	s_mov_b32 s7, 0xc000
	s_mov_b32 s8, 0x12000
	s_mov_b32 s9, 0x18000
	s_mov_b32 s10, 0x1e000
	s_mov_b32 s11, 0x24000
	s_mov_b32 s14, 0x2a000
	s_mov_b32 s15, 0x30000
	s_mov_b32 s23, 0x36000
	s_mov_b32 s33, 0x3c000
	s_mov_b32 s36, 0x42000
	s_mov_b32 s37, 0x48000
	s_mov_b32 s38, 0x4e000
	s_mov_b32 s39, 0x54000
	s_mov_b32 s40, 0x5a000
	v_mov_b32_e32 v17, 0x36000
	s_mov_b32 s41, s19
	s_mov_b32 s98, 0
	s_mov_b32 s99, 0x180000
	s_mov_b32 s100, 0
	s_cmpk_eq_i32 s18, 0x800
	s_cselect_b32 s101, 1, 0
	s_branch .LBB0_26
.LBB0_25:
	v_lshl_add_u64 v[2:3], v[2:3], 2, s[92:93]
	v_mad_i64_i32 v[2:3], s[4:5], s42, v17, v[2:3]
	v_add_co_u32_e32 v8, vcc, 0x6000, v2
	global_atomic_add_f32 v[2:3], v12, off
	s_nop 0
	v_addc_co_u32_e32 v9, vcc, 0, v3, vcc
	global_atomic_add_f32 v[8:9], v13, off
	v_add_co_u32_e32 v8, vcc, 0xc000, v2
	s_add_i32 s41, s41, s18
	s_nop 0
	v_addc_co_u32_e32 v9, vcc, 0, v3, vcc
	global_atomic_add_f32 v[8:9], v10, off
	v_add_co_u32_e32 v8, vcc, 0x12000, v2
	s_cmpk_gt_i32 s41, 0xbff
	s_nop 0
	v_addc_co_u32_e32 v9, vcc, 0, v3, vcc
	global_atomic_add_f32 v[8:9], v11, off
	v_add_co_u32_e32 v8, vcc, 0x18000, v2
	s_nop 1
	v_addc_co_u32_e32 v9, vcc, 0, v3, vcc
	global_atomic_add_f32 v[8:9], v6, off
	v_add_co_u32_e32 v8, vcc, 0x1e000, v2
	s_nop 1
	v_addc_co_u32_e32 v9, vcc, 0, v3, vcc
	v_add_co_u32_e32 v6, vcc, 0x24000, v2
	global_atomic_add_f32 v[8:9], v7, off
	s_nop 0
	v_addc_co_u32_e32 v7, vcc, 0, v3, vcc
	global_atomic_add_f32 v[6:7], v4, off
	v_add_co_u32_e32 v6, vcc, 0x2a000, v2
	s_nop 1
	v_addc_co_u32_e32 v7, vcc, 0, v3, vcc
	v_add_co_u32_e32 v2, vcc, 0x30000, v2
	global_atomic_add_f32 v[6:7], v5, off
	s_nop 0
	v_addc_co_u32_e32 v3, vcc, 0, v3, vcc
	global_atomic_add_f32 v[2:3], v18, off
	s_cmpk_lg_i32 s101, 0
	s_cbranch_scc1 mod_bal
	s_cmpk_gt_i32 s41, 0xbff
	s_cbranch_scc1 .LBB0_30
	s_branch .LBB0_26
mod_bal:
	s_add_i32 s98, s98, 1
	s_cmpk_gt_i32 s98, 1
	s_cbranch_scc1 .LBB0_30
	s_lshr_b32 s41, s19, 1
	s_addk_i32 s41, 0x800
	s_and_b32 s100, s19, 1
	s_mul_i32 s100, s100, 0xc0000
	s_add_u32 s99, s100, 0xc0000
.LBB0_26:
	s_ashr_i32 s4, s41, 31
	s_lshr_b32 s4, s4, 28
	s_add_i32 s4, s41, s4
	s_ashr_i32 s5, s4, 4
	s_and_b32 s4, s4, -16
	s_sub_i32 s12, s41, s4
	s_mul_hi_i32 s4, s5, 0x2aaaaaab
	s_lshr_b32 s13, s4, 31
	s_lshr_b32 s4, s4, 4
	s_add_i32 s4, s4, s13
	s_mulk_i32 s4, 0x60
	s_sub_i32 s4, s5, s4
	s_mul_hi_i32 s5, s41, 0x2aaaaaab
	s_lshr_b32 s13, s5, 31
	s_ashr_i32 s5, s5, 8
	s_add_i32 s42, s5, s13
	s_waitcnt vmcnt(0)
	v_lshl_or_b32 v2, s4, 6, v16
	s_mul_i32 s4, s12, 0x60000
	s_mul_i32 s43, s42, 0x1800000
	s_ashr_i32 s5, s4, 31
	s_mul_hi_i32 s13, s42, 0x1800000
	s_add_u32 s43, s24, s43
	s_addc_u32 s13, s25, s13
	s_lshl_b64 s[4:5], s[4:5], 2
	s_add_u32 s4, s43, s4
	v_ashrrev_i32_e32 v3, 31, v2
	s_addc_u32 s5, s13, s5
	v_lshl_add_u64 v[8:9], v[2:3], 2, s[4:5]
	s_lshl_b32 s4, s12, 8
	s_cmp_lg_u32 s100, 0
	s_cselect_b32 s5, 0x80, 0
	v_mov_b32_e32 v12, 0
	s_add_i32 s13, s4, s5
	s_mov_b32 s4, s100
	s_mov_b32 s5, 0
	v_mov_b32_e32 v13, v12
	v_mov_b32_e32 v10, v12
	v_mov_b32_e32 v11, v12
	v_mov_b32_e32 v6, v12
	v_mov_b32_e32 v7, v12
	v_mov_b32_e32 v4, v12
	v_mov_b32_e32 v5, v12
	v_mov_b32_e32 v18, v12
.LBB0_27:
	v_lshl_add_u64 v[14:15], v[8:9], 0, s[4:5]
	v_add_co_u32_e32 v166, vcc, s6, v14
	v_mov_b32_e32 v19, s13
	s_nop 0
	v_addc_co_u32_e32 v167, vcc, 0, v15, vcc
	v_add_co_u32_e32 v168, vcc, s7, v14
	ds_read_b128 v[20:23], v19
	ds_read_b128 v[24:27], v19 offset:16
	ds_read_b128 v[28:31], v19 offset:4096
	ds_read_b128 v[32:35], v19 offset:4112
	ds_read_b128 v[36:39], v19 offset:8192
	ds_read_b128 v[40:43], v19 offset:8208
	ds_read_b128 v[44:47], v19 offset:12288
	ds_read_b128 v[48:51], v19 offset:12304
	ds_read_b128 v[52:55], v19 offset:16384
	ds_read_b128 v[56:59], v19 offset:16400
	ds_read_b128 v[60:63], v19 offset:20480
	ds_read_b128 v[64:67], v19 offset:20496
	ds_read_b128 v[68:71], v19 offset:24576
	ds_read_b128 v[72:75], v19 offset:24592
	ds_read_b128 v[76:79], v19 offset:28672
	ds_read_b128 v[80:83], v19 offset:28688
	v_addc_co_u32_e32 v169, vcc, 0, v15, vcc
	v_add_co_u32_e32 v170, vcc, s8, v14
	global_load_dword v164, v[14:15], off nt
	s_nop 0
	v_addc_co_u32_e32 v171, vcc, 0, v15, vcc
	v_add_co_u32_e32 v172, vcc, s9, v14
	ds_read_b128 v[84:87], v19 offset:32768
	ds_read_b128 v[88:91], v19 offset:32784
	ds_read_b128 v[92:95], v19 offset:32
	ds_read_b128 v[96:99], v19 offset:48
	ds_read_b128 v[100:103], v19 offset:4128
	ds_read_b128 v[104:107], v19 offset:4144
	ds_read_b128 v[108:111], v19 offset:8224
	ds_read_b128 v[112:115], v19 offset:8240
	ds_read_b128 v[116:119], v19 offset:12320
	ds_read_b128 v[120:123], v19 offset:12336
	ds_read_b128 v[124:127], v19 offset:16416
	ds_read_b128 v[128:131], v19 offset:16432
	ds_read_b128 v[132:135], v19 offset:20512
	ds_read_b128 v[136:139], v19 offset:20528
	ds_read_b128 v[140:143], v19 offset:24608
	ds_read_b128 v[144:147], v19 offset:24624
	ds_read_b128 v[148:151], v19 offset:28704
	ds_read_b128 v[152:155], v19 offset:28720
	v_addc_co_u32_e32 v173, vcc, 0, v15, vcc
	v_add_co_u32_e32 v174, vcc, s10, v14
	ds_read_b128 v[156:159], v19 offset:32800
	ds_read_b128 v[160:163], v19 offset:32816
	v_addc_co_u32_e32 v175, vcc, 0, v15, vcc
	v_add_co_u32_e32 v176, vcc, s11, v14
	s_waitcnt lgkmcnt(14)
	v_mov_b32_e32 v194, v20
	v_addc_co_u32_e32 v177, vcc, 0, v15, vcc
	v_add_co_u32_e32 v178, vcc, s14, v14
	v_mov_b32_e32 v195, v28
	s_nop 0
	v_addc_co_u32_e32 v179, vcc, 0, v15, vcc
	v_add_co_u32_e32 v180, vcc, s15, v14
	v_mov_b32_e32 v28, v21
	s_nop 0
	v_addc_co_u32_e32 v181, vcc, 0, v15, vcc
	v_add_co_u32_e32 v182, vcc, s23, v14
	v_mov_b32_e32 v20, v22
	s_nop 0
	v_addc_co_u32_e32 v183, vcc, 0, v15, vcc
	v_add_co_u32_e32 v184, vcc, s33, v14
	v_mov_b32_e32 v21, v30
	s_nop 0
	v_addc_co_u32_e32 v185, vcc, 0, v15, vcc
	v_add_co_u32_e32 v186, vcc, s36, v14
	v_mov_b32_e32 v30, v23
	s_nop 0
	v_addc_co_u32_e32 v187, vcc, 0, v15, vcc
	v_add_co_u32_e32 v188, vcc, s37, v14
	v_mov_b32_e32 v22, v36
	s_nop 0
	v_addc_co_u32_e32 v189, vcc, 0, v15, vcc
	v_add_co_u32_e32 v190, vcc, s38, v14
	v_mov_b32_e32 v23, v44
	s_nop 0
	v_addc_co_u32_e32 v191, vcc, 0, v15, vcc
	v_add_co_u32_e32 v192, vcc, s39, v14
	v_mov_b32_e32 v44, v37
	s_nop 0
	v_addc_co_u32_e32 v193, vcc, 0, v15, vcc
	v_add_co_u32_e32 v14, vcc, s40, v14
	v_mov_b32_e32 v36, v38
	s_nop 0
	v_addc_co_u32_e32 v15, vcc, 0, v15, vcc
	global_load_dword v166, v[166:167], off nt
	s_nop 0
	global_load_dword v168, v[168:169], off nt
	s_nop 0
	global_load_dword v170, v[170:171], off nt
	s_nop 0
	global_load_dword v172, v[172:173], off nt
	s_nop 0
	global_load_dword v174, v[174:175], off nt
	s_nop 0
	global_load_dword v176, v[176:177], off nt
	s_nop 0
	global_load_dword v178, v[178:179], off nt
	s_nop 0
	global_load_dword v180, v[180:181], off nt
	s_nop 0
	global_load_dword v182, v[182:183], off nt
	s_nop 0
	global_load_dword v184, v[184:185], off nt
	s_nop 0
	global_load_dword v186, v[186:187], off nt
	s_nop 0
	global_load_dword v188, v[188:189], off nt
	s_nop 0
	global_load_dword v190, v[190:191], off nt
	s_nop 0
	global_load_dword v192, v[192:193], off nt
	s_nop 0
	global_load_dword v14, v[14:15], off nt
	v_mov_b32_e32 v37, v46
	v_mov_b32_e32 v46, v39
	v_mov_b32_e32 v38, v52
	v_mov_b32_e32 v39, v60
	v_mov_b32_e32 v60, v53
	v_mov_b32_e32 v52, v54
	v_mov_b32_e32 v53, v62
	v_mov_b32_e32 v62, v55
	v_mov_b32_e32 v54, v68
	v_mov_b32_e32 v55, v76
	v_mov_b32_e32 v76, v69
	v_mov_b32_e32 v68, v70
	v_mov_b32_e32 v69, v78
	v_mov_b32_e32 v78, v71
	v_mov_b32_e32 v70, v24
	v_mov_b32_e32 v71, v32
	s_waitcnt vmcnt(15)
	v_pk_fma_f32 v[12:13], v[164:165], v[194:195], v[12:13] op_sel_hi:[0,1,1]
	v_pk_fma_f32 v[10:11], v[164:165], v[22:23], v[10:11] op_sel_hi:[0,1,1]
	v_pk_fma_f32 v[6:7], v[164:165], v[38:39], v[6:7] op_sel_hi:[0,1,1]
	v_pk_fma_f32 v[4:5], v[164:165], v[54:55], v[4:5] op_sel_hi:[0,1,1]
	v_fmac_f32_e32 v18, v164, v84
	v_mov_b32_e32 v32, v25
	v_mov_b32_e32 v24, v26
	v_mov_b32_e32 v25, v34
	v_mov_b32_e32 v34, v27
	v_mov_b32_e32 v26, v40
	v_mov_b32_e32 v27, v48
	v_mov_b32_e32 v48, v41
	v_mov_b32_e32 v40, v42
	v_mov_b32_e32 v41, v50
	v_mov_b32_e32 v50, v43
	v_mov_b32_e32 v42, v56
	v_mov_b32_e32 v43, v64
	v_mov_b32_e32 v64, v57
	v_mov_b32_e32 v56, v58
	v_mov_b32_e32 v57, v66
	v_mov_b32_e32 v66, v59
	v_mov_b32_e32 v58, v72
	v_mov_b32_e32 v59, v80
	v_mov_b32_e32 v80, v73
	v_mov_b32_e32 v72, v74
	v_mov_b32_e32 v73, v82
	v_mov_b32_e32 v82, v75
	v_mov_b32_e32 v74, v92
	v_mov_b32_e32 v75, v100
	v_mov_b32_e32 v100, v93
	v_mov_b32_e32 v92, v94
	v_mov_b32_e32 v93, v102
	v_mov_b32_e32 v102, v95
	s_waitcnt lgkmcnt(13)
	v_mov_b32_e32 v94, v108
	s_waitcnt lgkmcnt(11)
	v_mov_b32_e32 v95, v116
	v_mov_b32_e32 v116, v109
	v_mov_b32_e32 v108, v110
	v_mov_b32_e32 v109, v118
	v_mov_b32_e32 v118, v111
	s_waitcnt lgkmcnt(9)
	v_mov_b32_e32 v110, v124
	s_waitcnt lgkmcnt(7)
	v_mov_b32_e32 v111, v132
	v_mov_b32_e32 v132, v125
	v_mov_b32_e32 v124, v126
	v_mov_b32_e32 v125, v134
	v_mov_b32_e32 v134, v127
	s_waitcnt lgkmcnt(5)
	v_mov_b32_e32 v126, v140
	s_waitcnt lgkmcnt(3)
	v_mov_b32_e32 v127, v148
	v_mov_b32_e32 v148, v141
	v_mov_b32_e32 v140, v142
	s_waitcnt vmcnt(14)
	v_pk_fma_f32 v[12:13], v[166:167], v[28:29], v[12:13] op_sel_hi:[0,1,1]
	v_pk_fma_f32 v[10:11], v[166:167], v[44:45], v[10:11] op_sel_hi:[0,1,1]
	v_pk_fma_f32 v[6:7], v[166:167], v[60:61], v[6:7] op_sel_hi:[0,1,1]
	v_pk_fma_f32 v[4:5], v[166:167], v[76:77], v[4:5] op_sel_hi:[0,1,1]
	v_fmac_f32_e32 v18, v166, v85
	s_waitcnt vmcnt(13)
	v_pk_fma_f32 v[12:13], v[168:169], v[20:21], v[12:13] op_sel_hi:[0,1,1]
	v_pk_fma_f32 v[10:11], v[168:169], v[36:37], v[10:11] op_sel_hi:[0,1,1]
	v_pk_fma_f32 v[6:7], v[168:169], v[52:53], v[6:7] op_sel_hi:[0,1,1]
	v_pk_fma_f32 v[4:5], v[168:169], v[68:69], v[4:5] op_sel_hi:[0,1,1]
	v_fmac_f32_e32 v18, v168, v86
	s_waitcnt vmcnt(12)
	v_pk_fma_f32 v[12:13], v[170:171], v[30:31], v[12:13] op_sel_hi:[0,1,1]
	v_pk_fma_f32 v[10:11], v[170:171], v[46:47], v[10:11] op_sel_hi:[0,1,1]
	v_pk_fma_f32 v[6:7], v[170:171], v[62:63], v[6:7] op_sel_hi:[0,1,1]
	v_pk_fma_f32 v[4:5], v[170:171], v[78:79], v[4:5] op_sel_hi:[0,1,1]
	v_fmac_f32_e32 v18, v170, v87
	s_waitcnt vmcnt(11)
	v_pk_fma_f32 v[12:13], v[172:173], v[70:71], v[12:13] op_sel_hi:[0,1,1]
	v_pk_fma_f32 v[10:11], v[172:173], v[26:27], v[10:11] op_sel_hi:[0,1,1]
	v_pk_fma_f32 v[6:7], v[172:173], v[42:43], v[6:7] op_sel_hi:[0,1,1]
	v_pk_fma_f32 v[4:5], v[172:173], v[58:59], v[4:5] op_sel_hi:[0,1,1]
	v_fmac_f32_e32 v18, v172, v88
	s_waitcnt vmcnt(10)
	v_pk_fma_f32 v[12:13], v[174:175], v[32:33], v[12:13] op_sel_hi:[0,1,1]
	v_pk_fma_f32 v[10:11], v[174:175], v[48:49], v[10:11] op_sel_hi:[0,1,1]
	v_pk_fma_f32 v[6:7], v[174:175], v[64:65], v[6:7] op_sel_hi:[0,1,1]
	v_pk_fma_f32 v[4:5], v[174:175], v[80:81], v[4:5] op_sel_hi:[0,1,1]
	v_fmac_f32_e32 v18, v174, v89
	s_waitcnt vmcnt(9)
	v_pk_fma_f32 v[12:13], v[176:177], v[24:25], v[12:13] op_sel_hi:[0,1,1]
	v_pk_fma_f32 v[10:11], v[176:177], v[40:41], v[10:11] op_sel_hi:[0,1,1]
	v_pk_fma_f32 v[6:7], v[176:177], v[56:57], v[6:7] op_sel_hi:[0,1,1]
	v_pk_fma_f32 v[4:5], v[176:177], v[72:73], v[4:5] op_sel_hi:[0,1,1]
	v_fmac_f32_e32 v18, v176, v90
	s_waitcnt vmcnt(8)
	v_pk_fma_f32 v[12:13], v[178:179], v[34:35], v[12:13] op_sel_hi:[0,1,1]
	v_pk_fma_f32 v[10:11], v[178:179], v[50:51], v[10:11] op_sel_hi:[0,1,1]
	v_pk_fma_f32 v[6:7], v[178:179], v[66:67], v[6:7] op_sel_hi:[0,1,1]
	v_pk_fma_f32 v[4:5], v[178:179], v[82:83], v[4:5] op_sel_hi:[0,1,1]
	v_fmac_f32_e32 v18, v178, v91
	s_waitcnt vmcnt(7)
	v_pk_fma_f32 v[12:13], v[180:181], v[74:75], v[12:13] op_sel_hi:[0,1,1]
	v_pk_fma_f32 v[10:11], v[180:181], v[94:95], v[10:11] op_sel_hi:[0,1,1]
	v_pk_fma_f32 v[6:7], v[180:181], v[110:111], v[6:7] op_sel_hi:[0,1,1]
	v_pk_fma_f32 v[4:5], v[180:181], v[126:127], v[4:5] op_sel_hi:[0,1,1]
	s_waitcnt lgkmcnt(1)
	v_fmac_f32_e32 v18, v180, v156
	v_mov_b32_e32 v141, v150
	s_waitcnt vmcnt(6)
	v_pk_fma_f32 v[12:13], v[182:183], v[100:101], v[12:13] op_sel_hi:[0,1,1]
	v_pk_fma_f32 v[10:11], v[182:183], v[116:117], v[10:11] op_sel_hi:[0,1,1]
	v_pk_fma_f32 v[6:7], v[182:183], v[132:133], v[6:7] op_sel_hi:[0,1,1]
	v_pk_fma_f32 v[4:5], v[182:183], v[148:149], v[4:5] op_sel_hi:[0,1,1]
	v_fmac_f32_e32 v18, v182, v157
	v_mov_b32_e32 v150, v143
	s_waitcnt vmcnt(5)
	v_pk_fma_f32 v[12:13], v[184:185], v[92:93], v[12:13] op_sel_hi:[0,1,1]
	v_pk_fma_f32 v[10:11], v[184:185], v[108:109], v[10:11] op_sel_hi:[0,1,1]
	v_pk_fma_f32 v[6:7], v[184:185], v[124:125], v[6:7] op_sel_hi:[0,1,1]
	v_pk_fma_f32 v[4:5], v[184:185], v[140:141], v[4:5] op_sel_hi:[0,1,1]
	v_fmac_f32_e32 v18, v184, v158
	v_mov_b32_e32 v142, v96
	v_mov_b32_e32 v143, v104
	v_mov_b32_e32 v104, v97
	v_mov_b32_e32 v96, v98
	v_mov_b32_e32 v97, v106
	v_mov_b32_e32 v106, v99
	v_mov_b32_e32 v98, v112
	v_mov_b32_e32 v99, v120
	v_mov_b32_e32 v120, v113
	v_mov_b32_e32 v112, v114
	v_mov_b32_e32 v113, v122
	v_mov_b32_e32 v122, v115
	v_mov_b32_e32 v114, v128
	v_mov_b32_e32 v115, v136
	v_mov_b32_e32 v136, v129
	v_mov_b32_e32 v128, v130
	v_mov_b32_e32 v129, v138
	v_mov_b32_e32 v138, v131
	v_mov_b32_e32 v130, v144
	v_mov_b32_e32 v131, v152
	s_waitcnt vmcnt(4)
	v_pk_fma_f32 v[12:13], v[186:187], v[102:103], v[12:13] op_sel_hi:[0,1,1]
	v_pk_fma_f32 v[10:11], v[186:187], v[118:119], v[10:11] op_sel_hi:[0,1,1]
	v_pk_fma_f32 v[6:7], v[186:187], v[134:135], v[6:7] op_sel_hi:[0,1,1]
	v_pk_fma_f32 v[4:5], v[186:187], v[150:151], v[4:5] op_sel_hi:[0,1,1]
	v_fmac_f32_e32 v18, v186, v159
	v_mov_b32_e32 v152, v145
	s_waitcnt vmcnt(3)
	v_pk_fma_f32 v[12:13], v[188:189], v[142:143], v[12:13] op_sel_hi:[0,1,1]
	v_pk_fma_f32 v[10:11], v[188:189], v[98:99], v[10:11] op_sel_hi:[0,1,1]
	v_pk_fma_f32 v[6:7], v[188:189], v[114:115], v[6:7] op_sel_hi:[0,1,1]
	v_pk_fma_f32 v[4:5], v[188:189], v[130:131], v[4:5] op_sel_hi:[0,1,1]
	s_waitcnt lgkmcnt(0)
	v_fmac_f32_e32 v18, v188, v160
	s_add_u32 s4, s4, 0x60000
	v_mov_b32_e32 v144, v146
	v_mov_b32_e32 v145, v154
	s_waitcnt vmcnt(2)
	v_pk_fma_f32 v[12:13], v[190:191], v[104:105], v[12:13] op_sel_hi:[0,1,1]
	v_pk_fma_f32 v[10:11], v[190:191], v[120:121], v[10:11] op_sel_hi:[0,1,1]
	v_pk_fma_f32 v[6:7], v[190:191], v[136:137], v[6:7] op_sel_hi:[0,1,1]
	v_pk_fma_f32 v[4:5], v[190:191], v[152:153], v[4:5] op_sel_hi:[0,1,1]
	v_fmac_f32_e32 v18, v190, v161
	s_addc_u32 s5, s5, 0
	s_add_i32 s13, s13, 64
	v_mov_b32_e32 v154, v147
	s_waitcnt vmcnt(1)
	v_pk_fma_f32 v[12:13], v[192:193], v[96:97], v[12:13] op_sel_hi:[0,1,1]
	v_pk_fma_f32 v[10:11], v[192:193], v[112:113], v[10:11] op_sel_hi:[0,1,1]
	v_pk_fma_f32 v[6:7], v[192:193], v[128:129], v[6:7] op_sel_hi:[0,1,1]
	v_pk_fma_f32 v[4:5], v[192:193], v[144:145], v[4:5] op_sel_hi:[0,1,1]
	v_fmac_f32_e32 v18, v192, v162
	s_cmp_eq_u32 s4, s99
	s_waitcnt vmcnt(0)
	v_pk_fma_f32 v[12:13], v[14:15], v[106:107], v[12:13] op_sel_hi:[0,1,1]
	v_pk_fma_f32 v[10:11], v[14:15], v[122:123], v[10:11] op_sel_hi:[0,1,1]
	v_pk_fma_f32 v[6:7], v[14:15], v[138:139], v[6:7] op_sel_hi:[0,1,1]
	v_pk_fma_f32 v[4:5], v[14:15], v[154:155], v[4:5] op_sel_hi:[0,1,1]
	v_fmac_f32_e32 v18, v14, v163
	s_cbranch_scc0 .LBB0_27
	s_or_b32 s5, s12, s100
	s_cmp_eq_u32 s5, 0
	s_cbranch_scc0 .LBB0_25
	s_mul_i32 s4, s42, 0x1800
	v_add_u32_e32 v8, s4, v2
	v_ashrrev_i32_e32 v9, 31, v8
	v_lshl_add_u64 v[8:9], v[8:9], 2, s[26:27]
	global_load_dword v8, v[8:9], off
	s_waitcnt vmcnt(0)
	v_pk_add_f32 v[12:13], v[12:13], v[8:9] op_sel_hi:[1,0]
	v_pk_add_f32 v[10:11], v[10:11], v[8:9] op_sel_hi:[1,0]
	v_pk_add_f32 v[6:7], v[6:7], v[8:9] op_sel_hi:[1,0]
	v_pk_add_f32 v[4:5], v[4:5], v[8:9] op_sel_hi:[1,0]
	v_add_f32_e32 v18, v18, v8
	s_branch .LBB0_25
